# P2/P8 round order reversed (most recently written ACT rows first, MALL reuse)
# speedup vs baseline: 1.0069x; 1.0069x over previous
;     __host__ __device__ bool next(int i, Unit& u) const {
;         const long L = (long)i * G + c; if (L >= nwg) return false;
;         int wgid = (int)L; { const int q = nwg / NXCD, r = nwg % NXCD, xcd = wgid % NXCD, off = wgid / NXCD; wgid = (xcd < r ? xcd * (q + 1) : r * (q + 1) + (xcd - r) * q) + off; }
;         const int nig = WGM * nN, gid = wgid / nig, fm = gid * WGM, gsz = (nM - fm) < WGM ? (nM - fm) : WGM;
;         u.pm = fm + ((wgid % nig) % gsz); u.pn = (wgid % nig) / gsz; return true;
; template <class Epi, class Sched, bool ALIGN_EPI = false, bool SP2 = false>
; __device__ __forceinline__ void gemm_phase(PG8_LAS unsigned char* lds, const Gemm g, const Sched& S, const Epi& E, const int tid_arg) {
;     ...
;     Unit cur, nxt; int ui = 0;
;     if (!S.next(0, cur)) return;
.LBB0_241:
	s_or_b64 exec, exec, s[4:5]
	s_cmpk_lt_i32 s60, 0x200
	s_mov_b64 s[4:5], 0
	s_cselect_b64 s[10:11], -1, 0
	s_mov_b64 s[6:7], s[90:91]
	s_mov_b64 s[8:9], s[90:91]
	v_mov_b32_e32 v10, v201
	s_waitcnt lgkmcnt(0)
	s_barrier
	s_and_b64 vcc, exec, s[10:11]
	v_readfirstlane_b32 s12, v10
	s_cbranch_vccz .LBB0_243
	s_lshr_b32 s1, s61, 29
	s_add_i32 s1, s60, s1
	s_ashr_i32 s2, s1, 3
	s_and_b32 s1, s1, -8
	s_sub_i32 s1, s60, s1
	s_lshl_b32 s13, s1, 6
	s_mul_i32 s3, s1, 0x41
	s_cmp_lt_i32 s1, 0
	s_cselect_b32 s1, s3, s13
	s_add_i32 s1, s1, s2
	s_add_i32 s1, s1, 32
	s_ashr_i32 s2, s1, 31
	s_lshr_b32 s2, s2, 28
	s_add_i32 s2, s1, s2
	s_ashr_i32 s3, s2, 4
	s_and_b32 s2, s2, 0xfff0
	s_sub_i32 s1, s1, s2
	s_bfe_i32 s2, s1, 0x80000
	s_bfe_u32 s2, s2, 0x2000d
	s_add_i32 s2, s1, s2
	s_bfe_i32 s13, s2, 0x80000
	s_and_b32 s2, s2, 0xfc
	s_sub_i32 s1, s1, s2
	s_lshl_b32 s3, s3, 2
	s_sext_i32_i16 s13, s13
	s_sext_i32_i8 s1, s1
	s_add_i32 s30, s3, s1
	s_ashr_i32 s55, s13, 2

;     __host__ __device__ bool next(int i, Unit& u) const {
;         const long L = (long)i * G + c; if (L >= nwg) return false;
;         int wgid = (int)L; { const int q = nwg / NXCD, r = nwg % NXCD, xcd = wgid % NXCD, off = wgid / NXCD; wgid = (xcd < r ? xcd * (q + 1) : r * (q + 1) + (xcd - r) * q) + off; }
;         const int nig = WGM * nN, gid = wgid / nig, fm = gid * WGM, gsz = (nM - fm) < WGM ? (nM - fm) : WGM;
;         u.pm = fm + ((wgid % nig) % gsz); u.pn = (wgid % nig) / gsz; return true;
; template <class Epi, class Sched, bool ALIGN_EPI = false, bool SP2 = false>
; __device__ __forceinline__ void gemm_phase(PG8_LAS unsigned char* lds, const Gemm g, const Sched& S, const Epi& E, const int tid_arg) {
;     ...
;         const bool has_next = S.next(ui + 1, nxt);
;         const char* nA = has_next ? (const char*)g.A + (size_t)nxt.pm * tstep : cA; const char* nB = has_next ? (const char*)g.Bt + (size_t)nxt.pn * tstep : cB;
.LBB0_249:
	s_add_i32 s52, s52, 1
	s_mul_i32 s10, s52, s75
	s_mul_hi_u32 s11, s52, s74
	s_add_i32 s11, s11, s10
	s_mul_i32 s10, s52, s74
	s_add_u32 s10, s10, s60
	s_addc_u32 s11, s11, s61
	s_xor_b32 s10, s10, 0x100
	v_cmp_gt_i64_e32 vcc, s[10:11], v[144:145]
	v_cmp_lt_i64_e64 s[12:13], s[10:11], v[142:143]
	s_cbranch_vccnz .LBB0_255
	s_ashr_i32 s11, s10, 31
	s_lshr_b32 s11, s11, 29
	s_add_i32 s16, s10, s11
	s_and_b32 s11, s16, -8
	s_sub_i32 s28, s10, s11
	s_cmp_gt_i32 s28, -1
	s_mov_b64 s[10:11], -1
	s_cbranch_scc0 .LBB0_252
	s_lshl_b32 s29, s28, 6
	s_mov_b64 s[10:11], 0

; template <class Epi, class Sched, bool ALIGN_EPI = false, bool SP2 = false>
; __device__ __forceinline__ void gemm_phase(PG8_LAS unsigned char* lds, const Gemm g, const Sched& S, const Epi& E, const int tid_arg) {
;     ...
; #pragma unroll
;         for (int a = 0; a < 2; ++a)
; #pragma unroll
;             for (int b = 0; b < 2; ++b)
; #pragma unroll
;                 for (int m = 0; m < 4; ++m)
; #pragma unroll
;                     for (int n = 0; n < 2; ++n) acc[a][b][m][n] = (f32x4){0.f, 0.f, 0.f, 0.f};
.LBB0_259:
	s_add_u32 s16, s36, 0x100
	v_mov_b32_e32 v2, 0
	s_addc_u32 s31, s37, 0
	s_mov_b32 s56, -2
	s_waitcnt lgkmcnt(0)
	v_mov_b32_e32 v3, v2
	v_mov_b32_e32 v4, v2
	v_mov_b32_e32 v5, v2
	v_mov_b32_e32 v6, v2
	v_mov_b32_e32 v7, v2
	v_mov_b32_e32 v8, v2
	v_mov_b32_e32 v9, v2
	v_mov_b32_e32 v18, v2
	v_mov_b32_e32 v19, v2
	v_mov_b32_e32 v20, v2
	v_mov_b32_e32 v21, v2
	v_mov_b32_e32 v22, v2
	v_mov_b32_e32 v23, v2
	v_mov_b32_e32 v24, v2
	v_mov_b32_e32 v25, v2
	v_mov_b32_e32 v34, v2
	v_mov_b32_e32 v35, v2
	v_mov_b32_e32 v36, v2
	v_mov_b32_e32 v37, v2
	v_mov_b32_e32 v38, v2
	v_mov_b32_e32 v39, v2
	v_mov_b32_e32 v40, v2
	v_mov_b32_e32 v41, v2
	v_mov_b32_e32 v50, v2
	v_mov_b32_e32 v51, v2
	v_mov_b32_e32 v52, v2
	v_mov_b32_e32 v53, v2
	v_mov_b32_e32 v54, v2
	v_mov_b32_e32 v55, v2
	v_mov_b32_e32 v56, v2
	v_mov_b32_e32 v57, v2
	v_mov_b32_e32 v10, v2
	v_mov_b32_e32 v11, v2
	v_mov_b32_e32 v12, v2
	v_mov_b32_e32 v13, v2
	v_mov_b32_e32 v14, v2
	v_mov_b32_e32 v15, v2
	v_mov_b32_e32 v16, v2
	v_mov_b32_e32 v17, v2
	v_mov_b32_e32 v26, v2
	v_mov_b32_e32 v27, v2
	v_mov_b32_e32 v28, v2
	v_mov_b32_e32 v29, v2
	v_mov_b32_e32 v30, v2
	v_mov_b32_e32 v31, v2
	v_mov_b32_e32 v32, v2
	v_mov_b32_e32 v33, v2
	v_mov_b32_e32 v42, v2
	v_mov_b32_e32 v43, v2
	v_mov_b32_e32 v44, v2
	v_mov_b32_e32 v45, v2
	v_mov_b32_e32 v46, v2
	v_mov_b32_e32 v47, v2
	v_mov_b32_e32 v48, v2
	v_mov_b32_e32 v49, v2
	v_mov_b32_e32 v58, v2
	v_mov_b32_e32 v59, v2
	v_mov_b32_e32 v60, v2
	v_mov_b32_e32 v61, v2
	v_mov_b32_e32 v62, v2
	v_mov_b32_e32 v63, v2
	v_mov_b32_e32 v64, v2
	v_mov_b32_e32 v65, v2
	v_mov_b32_e32 v66, v2
	v_mov_b32_e32 v67, v2
	v_mov_b32_e32 v68, v2
	v_mov_b32_e32 v69, v2
	v_mov_b32_e32 v70, v2
	v_mov_b32_e32 v71, v2
	v_mov_b32_e32 v72, v2
	v_mov_b32_e32 v73, v2
	v_mov_b32_e32 v82, v2
	v_mov_b32_e32 v83, v2
	v_mov_b32_e32 v84, v2
	v_mov_b32_e32 v85, v2
	v_mov_b32_e32 v86, v2
	v_mov_b32_e32 v87, v2
	v_mov_b32_e32 v88, v2
	v_mov_b32_e32 v89, v2
	v_mov_b32_e32 v98, v2
	v_mov_b32_e32 v99, v2
	v_mov_b32_e32 v100, v2
	v_mov_b32_e32 v101, v2
	v_mov_b32_e32 v102, v2
	v_mov_b32_e32 v103, v2
	v_mov_b32_e32 v104, v2
	v_mov_b32_e32 v105, v2
	v_mov_b32_e32 v114, v2
	v_mov_b32_e32 v115, v2
	v_mov_b32_e32 v116, v2
	v_mov_b32_e32 v117, v2
	v_mov_b32_e32 v118, v2
	v_mov_b32_e32 v119, v2
	v_mov_b32_e32 v120, v2
	v_mov_b32_e32 v121, v2
	v_mov_b32_e32 v74, v2
	v_mov_b32_e32 v75, v2
	v_mov_b32_e32 v76, v2
	v_mov_b32_e32 v77, v2
	v_mov_b32_e32 v78, v2
	v_mov_b32_e32 v79, v2
	v_mov_b32_e32 v80, v2
	v_mov_b32_e32 v81, v2
	v_mov_b32_e32 v90, v2
	v_mov_b32_e32 v91, v2
	v_mov_b32_e32 v92, v2
	v_mov_b32_e32 v93, v2
	v_mov_b32_e32 v94, v2
	v_mov_b32_e32 v95, v2
	v_mov_b32_e32 v96, v2
	v_mov_b32_e32 v97, v2
	v_mov_b32_e32 v106, v2
	v_mov_b32_e32 v107, v2
	v_mov_b32_e32 v108, v2
	v_mov_b32_e32 v109, v2
	v_mov_b32_e32 v110, v2
	v_mov_b32_e32 v111, v2
	v_mov_b32_e32 v112, v2
	v_mov_b32_e32 v113, v2
	v_mov_b32_e32 v122, v2
	v_mov_b32_e32 v123, v2
	v_mov_b32_e32 v124, v2
	v_mov_b32_e32 v125, v2
	v_mov_b32_e32 v126, v2
	v_mov_b32_e32 v127, v2
	v_mov_b32_e32 v128, v2
	v_mov_b32_e32 v129, v2
	s_nop 0
	s_nop 0
	s_nop 0
	s_nop 0
	s_nop 0
	s_nop 0
	s_nop 0
	s_nop 0
	s_nop 0
	s_nop 0
	s_nop 0
	s_nop 0
	s_nop 0
	s_nop 0
	s_nop 0

; #define PG8_STAGE(bufoff, gbase, voff) do { _Pragma("unroll") for (int _i = 0; _i < 2; ++_i) \
;         __builtin_amdgcn_global_load_lds((const unsigned*)((const char*)(gbase) + (voff)[_i]), (PG8_LAS unsigned*)(lds + (bufoff) + ldsw + _i * 8192), 16, 0, 0); } while (0)
; #define PG8_WAIT_V(n) asm volatile("s_waitcnt vmcnt(" #n ")" ::: "memory")
; #define PG8_BAR __builtin_amdgcn_s_barrier()
; template <class Epi, class Sched, bool ALIGN_EPI = false, bool SP2 = false>
; __device__ __forceinline__ void gemm_phase(PG8_LAS unsigned char* lds, const Gemm g, const Sched& S, const Epi& E, const int tid_arg) {
;     ...
;     const int tid = tid_l, wid = __builtin_amdgcn_readfirstlane(tid >> 6), lane = tid & 63, wr = wid >> 2, wc = wid & 3, fr = lane & 15, fq = lane >> 4;
;     const int K = g.K, nt = K / BK;
;     unsigned voffA[2], voffB[2];
; #pragma unroll
;     for (int i = 0; i < 2; ++i) { int R, C; stage_rc(tid * 16 + i * 8192, R, C); const int Rb = Epi::PERM ? ((R & ~31) + perm32(R & 31)) : R;
;         voffA[i] = (unsigned)(R * K + C) * 2u; voffB[i] = (unsigned)(Rb * K + C) * 2u; }
;     const size_t kstep = (size_t)(BK * 2);
;     const size_t hstep = (size_t)HALF * K * 2;
;     const size_t tstep = 2 * hstep;
;     const unsigned ldsw = (unsigned)wid * 1024u;
;     const int aoff = lds_byte(wr * 64 + fr, fq * 8), boff = lds_byte(wc * 32 + fr, fq * 8);
;     ...
;     Unit cur, nxt; int ui = 0;
;     if (!S.next(0, cur)) return;
;     f32x4 acc[2][2][4][2];
; #pragma unroll
;     for (int a = 0; a < 2; ++a)
; #pragma unroll
;         for (int b = 0; b < 2; ++b)
; #pragma unroll
;             for (int m = 0; m < 4; ++m)
; #pragma unroll
;                 for (int n = 0; n < 2; ++n) acc[a][b][m][n] = (f32x4){0.f, 0.f, 0.f, 0.f};
;     bf16x8 At[4][2], B0[2][2], B1[2][2];
;     const char* cA = (const char*)g.A + (size_t)cur.pm * tstep; const char* cB = (const char*)g.Bt + (size_t)cur.pn * tstep;
;     S.a_ready(cur);
;     if constexpr (SP2) {
;         PG8_STAGE(PG8_SB(0, 0), cB, voffB); PG8_STAGE(PG8_SB(0, 1), cB + hstep, voffB); PG8_STAGE(PG8_SA(0, 0), cA, voffA); PG8_STAGE(PG8_SA(0, 1), cA + hstep, voffA);
;         if (wr == 1) PG8_BAR;
;         PG8_WAIT_V(2); PG8_BAR;
;         PG8_STAGE(PG8_SB(1, 0), cB + kstep, voffB); PG8_STAGE(PG8_SA(1, 0), cA + kstep, voffA); PG8_STAGE(PG8_SB(1, 1), cB + hstep + kstep, voffB);
.LBB0_1154:
	v_ashrrev_i32_e32 v1, 31, v8
	v_lshrrev_b32_e32 v1, 26, v1
	v_add_u32_e32 v1, v8, v1
	v_ashrrev_i32_e32 v9, 6, v1
	v_bfe_i32 v1, v8, 27, 1
	v_lshlrev_b32_e32 v0, 4, v8
	v_lshrrev_b32_e32 v1, 22, v1
	v_add_u32_e32 v1, v0, v1
	v_and_b32_e32 v1, 0xfffffc00, v1
	v_sub_u32_e32 v1, v0, v1
	v_lshrrev_b32_e32 v2, 4, v1
	v_bitop3_b32 v1, v2, v1, 32 bitop3:0x6c
	v_ashrrev_i32_e32 v3, 31, v1
	v_lshrrev_b32_e32 v3, 26, v3
	v_lshlrev_b32_e32 v2, 3, v9
	v_add_u32_e32 v3, v1, v3
	v_and_b32_e32 v2, -16, v2
	v_ashrrev_i32_e32 v11, 6, v3
	v_and_b32_e32 v3, 0xc0, v3
	v_add_u32_e32 v2, v11, v2
	v_lshlrev_b32_e32 v4, 5, v9
	v_sub_u32_e32 v1, v1, v3
	v_mov_b32_e32 v3, 1
	v_and_b32_e32 v10, 32, v4
	v_ashrrev_i16_sdwa v1, v3, sext(v1) dst_sel:DWORD dst_unused:UNUSED_PAD src0_sel:DWORD src1_sel:BYTE_0
	v_lshlrev_b32_e32 v4, 1, v2
	v_lshrrev_b32_e32 v5, 2, v2
	v_and_b32_e32 v6, 3, v11
	s_mov_b32 s11, 0xffffe0
	v_bfe_i32 v12, v1, 0, 16
	v_and_b32_e32 v4, 24, v4
	v_and_b32_e32 v5, 4, v5
	v_and_or_b32 v6, v2, s11, v6
	s_movk_i32 s6, 0xb00
	v_add_u32_e32 v1, v10, v12
	v_or3_b32 v4, v6, v5, v4
	v_mul_lo_u32 v2, v2, s6
	s_add_u32 s2, s4, 0x8c90000
	s_waitcnt vmcnt(8)
	v_add_lshl_u32 v128, v1, v2, 1
	v_mul_u32_u24_e32 v2, 0xb00, v4
	v_add_u32_e32 v0, 0x2000, v0
	v_readlane_b32 s13, v251, 15
	s_addc_u32 s3, s5, 0
	v_add_lshl_u32 v130, v2, v1, 1
	v_ashrrev_i32_e32 v1, 31, v0
	s_add_i32 s12, s12, s13
	s_add_i32 s12, s12, 32
	v_lshrrev_b32_e32 v1, 22, v1
	s_ashr_i32 s13, s12, 31
	v_add_u32_e32 v1, v0, v1
	s_lshr_b32 s13, s13, 28
	v_ashrrev_i32_e32 v13, 10, v1
	s_add_i32 s13, s12, s13
	v_mul_i32_i24_e32 v1, 0x400, v13
	s_ashr_i32 s14, s13, 4
	s_and_b32 s13, s13, -16
	v_sub_u32_e32 v0, v0, v1
	s_sub_i32 s12, s12, s13
	v_lshrrev_b32_e32 v1, 4, v0
	s_bfe_i32 s13, s12, 0x80000
	v_bitop3_b32 v0, v1, v0, 32 bitop3:0x6c
	s_bfe_u32 s13, s13, 0x2000d
	v_ashrrev_i32_e32 v2, 31, v0
	s_add_i32 s13, s12, s13
	v_lshrrev_b32_e32 v2, 26, v2
	s_bfe_i32 s15, s13, 0x80000
	s_and_b32 s13, s13, 0xfc
	v_lshlrev_b32_e32 v1, 3, v13
	v_add_u32_e32 v2, v0, v2
	s_sub_i32 s12, s12, s13
	v_and_b32_e32 v1, -16, v1
	v_ashrrev_i32_e32 v14, 6, v2
	v_lshlrev_b32_e32 v4, 5, v13
	s_lshl_b32 s14, s14, 2
	s_sext_i32_i16 s15, s15
	s_sext_i32_i8 s12, s12
	s_ashr_i32 s7, s10, 6
	v_add_u32_e32 v1, v14, v1
	v_and_b32_e32 v15, 32, v4
	v_and_b32_e32 v2, 0xc0, v2
	v_and_b32_e32 v4, 3, v14
	s_add_i32 s22, s14, s12
	s_ashr_i32 s12, s15, 2
	v_sub_u32_e32 v0, v0, v2
	v_and_or_b32 v4, v1, s11, v4
	s_ashr_i32 s11, s10, 8
	s_lshl_b32 s33, s7, 10
	s_lshr_b32 s18, s15, 2
	s_mul_hi_i32 s13, s12, 0x160000
	s_mul_i32 s12, s12, 0x160000
	v_ashrrev_i16_sdwa v0, v3, sext(v0) dst_sel:DWORD dst_unused:UNUSED_PAD src0_sel:DWORD src1_sel:BYTE_0
	v_lshlrev_b32_e32 v2, 1, v1
	v_lshrrev_b32_e32 v3, 2, v1
	s_add_u32 s26, s0, s12
	v_bfe_i32 v16, v0, 0, 16
	v_and_b32_e32 v2, 24, v2
	v_and_b32_e32 v3, 4, v3
	s_addc_u32 s27, s1, s13
	s_add_i32 s34, s33, 0
	v_add_u32_e32 v0, v15, v16
	v_or3_b32 v2, v4, v3, v2
	v_mul_lo_u32 v1, v1, s6
	s_add_i32 m0, s34, 0x10000
	v_add_lshl_u32 v132, v0, v1, 1
	v_mul_u32_u24_e32 v1, 0xb00, v2
	global_load_lds_dwordx4 v130, s[26:27]
	s_add_i32 m0, s34, 0x12000
	v_add_lshl_u32 v134, v1, v0, 1
	s_add_u32 s12, s26, 0xb0000
	global_load_lds_dwordx4 v134, s[26:27]
	s_addc_u32 s13, s27, 0
	s_add_i32 m0, s34, 0x14000
	s_mul_i32 s16, s22, 0x160000
	global_load_lds_dwordx4 v130, s[12:13]
	s_add_i32 m0, s34, 0x16000
	s_mul_hi_i32 s14, s22, 0x160000
	s_add_u32 s24, s2, s16
	s_addc_u32 s25, s3, s14
	s_add_i32 s35, s34, 0x2000
	global_load_lds_dwordx4 v134, s[12:13]
	s_mov_b32 m0, s34
	s_add_u32 s12, s24, 0xb0000
	global_load_lds_dwordx4 v128, s[24:25]
	s_mov_b32 m0, s35
	s_addc_u32 s13, s25, 0
	s_add_i32 s36, s34, 0x4000
	global_load_lds_dwordx4 v132, s[24:25]
	s_mov_b32 m0, s36
	s_add_i32 s37, s34, 0x6000
	global_load_lds_dwordx4 v128, s[12:13]
	s_mov_b32 m0, s37
	v_mov_b32_e32 v131, 0
	global_load_lds_dwordx4 v132, s[12:13]
	v_mov_b32_e32 v135, v131
	v_mov_b32_e32 v129, v131
	v_mov_b32_e32 v133, v131
	s_cmp_eq_u32 s11, 1
	s_mov_b32 s38, 0
	v_lshl_add_u64 v[6:7], s[26:27], 0, v[130:131]
	v_lshl_add_u64 v[4:5], s[26:27], 0, v[134:135]
	v_lshl_add_u64 v[0:1], s[24:25], 0, v[128:129]
	s_cselect_b64 s[12:13], -1, 0
	s_cmp_lg_u32 s11, 1
	v_lshl_add_u64 v[2:3], s[24:25], 0, v[132:133]
	s_cbranch_scc1 .LBB0_1156
	s_barrier

;     __host__ __device__ bool next(int i, Unit& u) const {
;         const long L = (long)i * G + c; if (L >= nwg) return false;
;         int wgid = (int)L; { const int q = nwg / NXCD, r = nwg % NXCD, xcd = wgid % NXCD, off = wgid / NXCD; wgid = (xcd < r ? xcd * (q + 1) : r * (q + 1) + (xcd - r) * q) + off; }
;         const int nig = WGM * nN, gid = wgid / nig, fm = gid * WGM, gsz = (nM - fm) < WGM ? (nM - fm) : WGM;
;         u.pm = fm + ((wgid % nig) % gsz); u.pn = (wgid % nig) / gsz; return true;
; template <class Epi, class Sched, bool ALIGN_EPI = false, bool SP2 = false>
; __device__ __forceinline__ void gemm_phase(PG8_LAS unsigned char* lds, const Gemm g, const Sched& S, const Epi& E, const int tid_arg) {
;     ...
;         const bool has_next = S.next(ui + 1, nxt);
;         const char* nA = has_next ? (const char*)g.A + (size_t)nxt.pm * tstep : cA; const char* nB = has_next ? (const char*)g.Bt + (size_t)nxt.pn * tstep : cB;
.LBB0_1159:
	s_add_i32 s38, s38, 1
	s_mul_i32 s6, s38, s75
	s_mul_hi_u32 s7, s38, s74
	s_add_i32 s7, s7, s6
	s_mul_i32 s6, s38, s74
	s_add_u32 s6, s6, s56
	s_addc_u32 s7, s7, s57
	s_xor_b32 s6, s6, 0x100
	v_cmp_gt_i64_e32 vcc, s[6:7], v[142:143]
	v_cmp_lt_i64_e64 s[10:11], s[6:7], v[140:141]
	s_cbranch_vccnz .LBB0_1165
	s_ashr_i32 s7, s6, 31
	s_lshr_b32 s7, s7, 29
	s_add_i32 s20, s6, s7
	s_and_b32 s7, s20, -8
	s_sub_i32 s21, s6, s7
	s_cmp_gt_i32 s21, -1
	s_mov_b64 s[6:7], -1
	s_cbranch_scc0 .LBB0_1162
	s_lshl_b32 s23, s21, 6
	s_mov_b64 s[6:7], 0

; template <class Epi, class Sched, bool ALIGN_EPI = false, bool SP2 = false>
; __device__ __forceinline__ void gemm_phase(PG8_LAS unsigned char* lds, const Gemm g, const Sched& S, const Epi& E, const int tid_arg) {
;     ...
; #pragma unroll
;         for (int a = 0; a < 2; ++a)
; #pragma unroll
;             for (int b = 0; b < 2; ++b)
; #pragma unroll
;                 for (int m = 0; m < 4; ++m)
; #pragma unroll
;                     for (int n = 0; n < 2; ++n) acc[a][b][m][n] = (f32x4){0.f, 0.f, 0.f, 0.f};
.LBB0_1169:
	s_add_u32 s23, s26, 0x100
	v_mov_b32_e32 v0, 0
	s_addc_u32 s46, s27, 0
	s_mov_b32 s47, -2
	v_mov_b32_e32 v1, v0
	v_mov_b32_e32 v2, v0
	v_mov_b32_e32 v3, v0
	v_mov_b32_e32 v4, v0
	v_mov_b32_e32 v5, v0
	v_mov_b32_e32 v6, v0
	v_mov_b32_e32 v7, v0
	v_mov_b32_e32 v16, v0
	v_mov_b32_e32 v17, v0
	v_mov_b32_e32 v18, v0
	v_mov_b32_e32 v19, v0
	v_mov_b32_e32 v20, v0
	v_mov_b32_e32 v21, v0
	v_mov_b32_e32 v22, v0
	v_mov_b32_e32 v23, v0
	v_mov_b32_e32 v32, v0
	v_mov_b32_e32 v33, v0
	v_mov_b32_e32 v34, v0
	v_mov_b32_e32 v35, v0
	v_mov_b32_e32 v36, v0
	v_mov_b32_e32 v37, v0
	v_mov_b32_e32 v38, v0
	v_mov_b32_e32 v39, v0
	v_mov_b32_e32 v48, v0
	v_mov_b32_e32 v49, v0
	v_mov_b32_e32 v50, v0
	v_mov_b32_e32 v51, v0
	v_mov_b32_e32 v52, v0
	v_mov_b32_e32 v53, v0
	v_mov_b32_e32 v54, v0
	v_mov_b32_e32 v55, v0
	v_mov_b32_e32 v8, v0
	v_mov_b32_e32 v9, v0
	v_mov_b32_e32 v10, v0
	v_mov_b32_e32 v11, v0
	v_mov_b32_e32 v12, v0
	v_mov_b32_e32 v13, v0
	v_mov_b32_e32 v14, v0
	v_mov_b32_e32 v15, v0
	v_mov_b32_e32 v24, v0
	v_mov_b32_e32 v25, v0
	v_mov_b32_e32 v26, v0
	v_mov_b32_e32 v27, v0
	v_mov_b32_e32 v28, v0
	v_mov_b32_e32 v29, v0
	v_mov_b32_e32 v30, v0
	v_mov_b32_e32 v31, v0
	v_mov_b32_e32 v40, v0
	v_mov_b32_e32 v41, v0
	v_mov_b32_e32 v42, v0
	v_mov_b32_e32 v43, v0
	v_mov_b32_e32 v44, v0
	v_mov_b32_e32 v45, v0
	v_mov_b32_e32 v46, v0
	v_mov_b32_e32 v47, v0
	v_mov_b32_e32 v56, v0
	v_mov_b32_e32 v57, v0
	v_mov_b32_e32 v58, v0
	v_mov_b32_e32 v59, v0
	v_mov_b32_e32 v60, v0
	v_mov_b32_e32 v61, v0
	v_mov_b32_e32 v62, v0
	v_mov_b32_e32 v63, v0
	v_mov_b32_e32 v64, v0
	v_mov_b32_e32 v65, v0
	v_mov_b32_e32 v66, v0
	v_mov_b32_e32 v67, v0
	v_mov_b32_e32 v68, v0
	v_mov_b32_e32 v69, v0
	v_mov_b32_e32 v70, v0
	v_mov_b32_e32 v71, v0
	v_mov_b32_e32 v80, v0
	v_mov_b32_e32 v81, v0
	v_mov_b32_e32 v82, v0
	v_mov_b32_e32 v83, v0
	v_mov_b32_e32 v84, v0
	v_mov_b32_e32 v85, v0
	v_mov_b32_e32 v86, v0
	v_mov_b32_e32 v87, v0
	v_mov_b32_e32 v96, v0
	v_mov_b32_e32 v97, v0
	v_mov_b32_e32 v98, v0
	v_mov_b32_e32 v99, v0
	v_mov_b32_e32 v100, v0
	v_mov_b32_e32 v101, v0
	v_mov_b32_e32 v102, v0
	v_mov_b32_e32 v103, v0
	v_mov_b32_e32 v112, v0
	v_mov_b32_e32 v113, v0
	v_mov_b32_e32 v114, v0
	v_mov_b32_e32 v115, v0
	v_mov_b32_e32 v116, v0
	v_mov_b32_e32 v117, v0
	v_mov_b32_e32 v118, v0
	v_mov_b32_e32 v119, v0
	v_mov_b32_e32 v72, v0
	v_mov_b32_e32 v73, v0
	v_mov_b32_e32 v74, v0
	v_mov_b32_e32 v75, v0
	v_mov_b32_e32 v76, v0
	v_mov_b32_e32 v77, v0
	v_mov_b32_e32 v78, v0
	v_mov_b32_e32 v79, v0
	v_mov_b32_e32 v88, v0
	v_mov_b32_e32 v89, v0
	v_mov_b32_e32 v90, v0
	v_mov_b32_e32 v91, v0
	v_mov_b32_e32 v92, v0
	v_mov_b32_e32 v93, v0
	v_mov_b32_e32 v94, v0
	v_mov_b32_e32 v95, v0
	v_mov_b32_e32 v104, v0
	v_mov_b32_e32 v105, v0
	v_mov_b32_e32 v106, v0
	v_mov_b32_e32 v107, v0
	v_mov_b32_e32 v108, v0
	v_mov_b32_e32 v109, v0
	v_mov_b32_e32 v110, v0
	v_mov_b32_e32 v111, v0
	v_mov_b32_e32 v120, v0
	v_mov_b32_e32 v121, v0
	v_mov_b32_e32 v122, v0
	v_mov_b32_e32 v123, v0
	v_mov_b32_e32 v124, v0
	v_mov_b32_e32 v125, v0
	v_mov_b32_e32 v126, v0
	v_mov_b32_e32 v127, v0
	s_nop 0
	s_nop 0
	s_nop 0
	s_nop 0
	s_nop 0
	s_nop 0
	s_nop 0
	s_nop 0
	s_nop 0
	s_nop 0
	s_nop 0
	s_nop 0
	s_nop 0
	s_nop 0
	s_nop 0
	s_nop 0
	s_nop 0
	s_nop 0
	s_nop 0
	s_nop 0
	s_nop 0
	s_nop 0
	s_nop 0
